# all load-hoisting and chain-splitting edits stacked on the staggered-attention version (S5 scan chains split, GLU epilogue loads ahead, transpose gain loads together)
# speedup vs baseline: 1.0015x; 1.0015x over previous
; #define LAS __attribute__((address_space(3)))
; __device__ __forceinline__ void transpose_tile(const float* src, int ld, int K, const float* gvec, bf16_t* dst, int kt, int nt, int mode, LAS float* tl) {
;     ...
;     for (int i = 0; i < 16; ++i) {
;         const int row = (tid >> 6) + 8 * i;
;         const float g = gvec ? gvec[k0 + row] : 1.f;
;         const int sw = ((row >> 3) & 15) << 1; LAS float* q = tl + row * 256;
;         q[(j) ^ sw] = v[i].x * g; q[(j + 1) ^ sw] = v[i].y * g; q[(j + 2) ^ sw] = v[i].z * g; q[(j + 3) ^ sw] = v[i].w * g;
;     }
.LBB0_202:
	v_add_u32_e32 v4, 0x78, v70
	v_lshrrev_b32_e32 v5, 2, v4
	v_lshl_add_u32 v4, v4, 10, 0
	v_bitop3_b32 v6, v5, v69, 30 bitop3:0x6c
	s_waitcnt vmcnt(0)
	v_mul_f32_e32 v0, v0, v95
	v_lshl_add_u32 v6, v6, 2, v4
	ds_write_b32 v6, v0
	v_mul_f32_e32 v0, v1, v95
	v_bitop3_b32 v1, v5, v73, 30 bitop3:0x6c
	v_lshl_add_u32 v1, v1, 2, v4
	ds_write_b32 v1, v0
	v_mul_f32_e32 v0, v2, v95
	v_bitop3_b32 v1, v5, v72, 30 bitop3:0x6c
	v_and_b32_e32 v2, 15, v68
	v_lshl_add_u32 v1, v1, 2, v4
	v_lshlrev_b32_e32 v10, 1, v2
	v_ashrrev_i32_e32 v12, 4, v68
	ds_write_b32 v1, v0
	v_bitop3_b32 v1, v5, v71, 30 bitop3:0x6c
	v_lshl_add_u32 v11, v2, 13, 0
	v_lshlrev_b32_e32 v136, 4, v2
	v_xor_b32_e32 v2, v10, v12
	v_mul_f32_e32 v0, v3, v95
	v_lshl_add_u32 v1, v1, 2, v4
	v_lshl_add_u32 v8, v2, 2, v11
	ds_write_b32 v1, v0
	s_waitcnt lgkmcnt(0)
	s_barrier
; __device__ __forceinline__ unsigned cvt_pk_bf16(float lo, float hi) { unsigned r; asm volatile("v_cvt_pk_bf16_f32 %0, %1, %2" : "=v"(r) : "v"(lo), "v"(hi)); return r; }
; __device__ __forceinline__ void transpose_tile(const float* src, int ld, int K, const float* gvec, bf16_t* dst, int kt, int nt, int mode, LAS float* tl) {
;     ...
;     __syncthreads();
; #pragma unroll
;     for (int jj = 0; jj < 8; ++jj) {
;         const int c = tid + 512 * jj; const int n = c >> 4, kc = c & 15;
;         float x[8];
; #pragma unroll
;         for (int i = 0; i < 8; ++i) x[i] = tl[(kc * 8 + i) * 256 + (n ^ (kc << 1))];
;         u32x4 w; w.x = cvt_pk_bf16(x[0], x[1]); w.y = cvt_pk_bf16(x[2], x[3]); w.z = cvt_pk_bf16(x[4], x[5]); w.w = cvt_pk_bf16(x[6], x[7]);
;         *(u32x4*)(dst + (size_t)(n0 + n) * K + k0 + kc * 8) = w;
;     }
	ds_read2st64_b32 v[2:3], v8 offset1:4
	ds_read2st64_b32 v[4:5], v8 offset0:8 offset1:12
	ds_read2st64_b32 v[6:7], v8 offset0:16 offset1:20
	ds_read2st64_b32 v[8:9], v8 offset0:24 offset1:28
	s_ashr_i32 s19, s18, 31
	s_waitcnt lgkmcnt(3)
	v_cvt_pk_bf16_f32 v2, v2, v3
	s_waitcnt lgkmcnt(2)
	v_cvt_pk_bf16_f32 v3, v4, v5
	s_waitcnt lgkmcnt(1)
	v_cvt_pk_bf16_f32 v4, v6, v7
	v_add_u32_e32 v6, s24, v12
	s_lshl_b64 s[6:7], s[18:19], 1
	v_ashrrev_i32_e32 v7, 31, v6
	v_lshl_add_u64 v[0:1], v[64:65], 0, s[6:7]
	s_waitcnt lgkmcnt(0)
	v_cvt_pk_bf16_f32 v5, v8, v9
	v_mul_lo_u32 v8, s16, v7
	v_mul_lo_u32 v9, s17, v6
	v_mad_u64_u32 v[6:7], s[6:7], s16, v6, 0
	v_lshl_add_u64 v[0:1], v[0:1], 0, v[136:137]
	v_add3_u32 v7, v7, v8, v9
	v_lshl_add_u64 v[6:7], v[6:7], 1, v[0:1]
	global_store_dwordx4 v[6:7], v[2:5], off
	v_readlane_b32 s3, v252, 0
	s_add_i32 s28, s28, s3
	v_add_u32_e32 v2, 0x200, v68
	v_ashrrev_i32_e32 v12, 4, v2
	v_xor_b32_e32 v2, v12, v10
	v_lshl_add_u32 v8, v2, 2, v11
	ds_read2st64_b32 v[2:3], v8 offset1:4
	ds_read2st64_b32 v[4:5], v8 offset0:8 offset1:12
	ds_read2st64_b32 v[6:7], v8 offset0:16 offset1:20
	ds_read2st64_b32 v[8:9], v8 offset0:24 offset1:28
	s_waitcnt lgkmcnt(3)
	v_cvt_pk_bf16_f32 v2, v2, v3
	s_waitcnt lgkmcnt(2)
	v_cvt_pk_bf16_f32 v3, v4, v5
	s_waitcnt lgkmcnt(1)
	v_cvt_pk_bf16_f32 v4, v6, v7
	v_add_u32_e32 v6, s24, v12
	v_ashrrev_i32_e32 v7, 31, v6
	s_waitcnt lgkmcnt(0)
	v_cvt_pk_bf16_f32 v5, v8, v9
	v_mul_lo_u32 v8, s16, v7
	v_mul_lo_u32 v9, s17, v6
	v_mad_u64_u32 v[6:7], s[6:7], s16, v6, 0
	v_add3_u32 v7, v7, v8, v9
	v_lshl_add_u64 v[6:7], v[6:7], 1, v[0:1]
	global_store_dwordx4 v[6:7], v[2:5], off
	s_cmpk_gt_i32 s28, 0xf47
	s_nop 0
	v_add_u32_e32 v2, 0x400, v68
	v_ashrrev_i32_e32 v12, 4, v2
	v_xor_b32_e32 v2, v12, v10
	v_lshl_add_u32 v8, v2, 2, v11
	ds_read2st64_b32 v[2:3], v8 offset1:4
	ds_read2st64_b32 v[4:5], v8 offset0:8 offset1:12
	ds_read2st64_b32 v[6:7], v8 offset0:16 offset1:20
	ds_read2st64_b32 v[8:9], v8 offset0:24 offset1:28
	s_waitcnt lgkmcnt(3)
	v_cvt_pk_bf16_f32 v2, v2, v3
	s_waitcnt lgkmcnt(2)
	v_cvt_pk_bf16_f32 v3, v4, v5
	s_waitcnt lgkmcnt(1)
	v_cvt_pk_bf16_f32 v4, v6, v7
	v_add_u32_e32 v6, s24, v12
	v_ashrrev_i32_e32 v7, 31, v6
	s_waitcnt lgkmcnt(0)
	v_cvt_pk_bf16_f32 v5, v8, v9
	v_mul_lo_u32 v8, s16, v7
	v_mul_lo_u32 v9, s17, v6
	v_mad_u64_u32 v[6:7], s[6:7], s16, v6, 0
	v_add3_u32 v7, v7, v8, v9
	v_lshl_add_u64 v[6:7], v[6:7], 1, v[0:1]
	global_store_dwordx4 v[6:7], v[2:5], off
	s_nop 1
	v_add_u32_e32 v2, 0x600, v68
	v_ashrrev_i32_e32 v12, 4, v2
	v_xor_b32_e32 v2, v12, v10
	v_lshl_add_u32 v8, v2, 2, v11
	ds_read2st64_b32 v[2:3], v8 offset1:4
	ds_read2st64_b32 v[4:5], v8 offset0:8 offset1:12
	ds_read2st64_b32 v[6:7], v8 offset0:16 offset1:20
	ds_read2st64_b32 v[8:9], v8 offset0:24 offset1:28
	s_waitcnt lgkmcnt(3)
	v_cvt_pk_bf16_f32 v2, v2, v3
	s_waitcnt lgkmcnt(2)
	v_cvt_pk_bf16_f32 v3, v4, v5
	s_waitcnt lgkmcnt(1)
	v_cvt_pk_bf16_f32 v4, v6, v7
	v_add_u32_e32 v6, s24, v12
	v_ashrrev_i32_e32 v7, 31, v6
	s_waitcnt lgkmcnt(0)
	v_cvt_pk_bf16_f32 v5, v8, v9
	v_mul_lo_u32 v8, s16, v7
	v_mul_lo_u32 v9, s17, v6
	v_mad_u64_u32 v[6:7], s[6:7], s16, v6, 0
	v_add3_u32 v7, v7, v8, v9
	v_lshl_add_u64 v[6:7], v[6:7], 1, v[0:1]
	global_store_dwordx4 v[6:7], v[2:5], off
	s_nop 1
	v_add_u32_e32 v2, 0x800, v68
	v_ashrrev_i32_e32 v12, 4, v2
	v_xor_b32_e32 v2, v12, v10
	v_lshl_add_u32 v8, v2, 2, v11
	ds_read2st64_b32 v[2:3], v8 offset1:4
	ds_read2st64_b32 v[4:5], v8 offset0:8 offset1:12
	ds_read2st64_b32 v[6:7], v8 offset0:16 offset1:20
	ds_read2st64_b32 v[8:9], v8 offset0:24 offset1:28
	s_waitcnt lgkmcnt(3)
	v_cvt_pk_bf16_f32 v2, v2, v3
	s_waitcnt lgkmcnt(2)
	v_cvt_pk_bf16_f32 v3, v4, v5
	s_waitcnt lgkmcnt(1)
	v_cvt_pk_bf16_f32 v4, v6, v7
	v_add_u32_e32 v6, s24, v12
	v_ashrrev_i32_e32 v7, 31, v6
	s_waitcnt lgkmcnt(0)
	v_cvt_pk_bf16_f32 v5, v8, v9
	v_mul_lo_u32 v8, s16, v7
	v_mul_lo_u32 v9, s17, v6
	v_mad_u64_u32 v[6:7], s[6:7], s16, v6, 0
	v_add3_u32 v7, v7, v8, v9
	v_lshl_add_u64 v[6:7], v[6:7], 1, v[0:1]
	global_store_dwordx4 v[6:7], v[2:5], off
	s_nop 1
	v_add_u32_e32 v2, 0xa00, v68
	v_ashrrev_i32_e32 v12, 4, v2
	v_xor_b32_e32 v2, v12, v10
	v_lshl_add_u32 v8, v2, 2, v11
	ds_read2st64_b32 v[2:3], v8 offset1:4
	ds_read2st64_b32 v[4:5], v8 offset0:8 offset1:12
	ds_read2st64_b32 v[6:7], v8 offset0:16 offset1:20
	ds_read2st64_b32 v[8:9], v8 offset0:24 offset1:28
	s_waitcnt lgkmcnt(3)
	v_cvt_pk_bf16_f32 v2, v2, v3
	s_waitcnt lgkmcnt(2)
	v_cvt_pk_bf16_f32 v3, v4, v5
	s_waitcnt lgkmcnt(1)
	v_cvt_pk_bf16_f32 v4, v6, v7
	v_add_u32_e32 v6, s24, v12
	v_ashrrev_i32_e32 v7, 31, v6
	s_waitcnt lgkmcnt(0)
	v_cvt_pk_bf16_f32 v5, v8, v9
	v_mul_lo_u32 v8, s16, v7
	v_mul_lo_u32 v9, s17, v6
	v_mad_u64_u32 v[6:7], s[6:7], s16, v6, 0
	v_add3_u32 v7, v7, v8, v9
	v_lshl_add_u64 v[6:7], v[6:7], 1, v[0:1]
	global_store_dwordx4 v[6:7], v[2:5], off
	s_nop 1
	v_add_u32_e32 v2, 0xc00, v68
	v_ashrrev_i32_e32 v12, 4, v2
	v_xor_b32_e32 v2, v12, v10
	v_lshl_add_u32 v8, v2, 2, v11
	ds_read2st64_b32 v[2:3], v8 offset1:4
	ds_read2st64_b32 v[4:5], v8 offset0:8 offset1:12
	ds_read2st64_b32 v[6:7], v8 offset0:16 offset1:20
	ds_read2st64_b32 v[8:9], v8 offset0:24 offset1:28
	s_waitcnt lgkmcnt(3)
	v_cvt_pk_bf16_f32 v2, v2, v3
	s_waitcnt lgkmcnt(2)
	v_cvt_pk_bf16_f32 v3, v4, v5
	s_waitcnt lgkmcnt(1)
	v_cvt_pk_bf16_f32 v4, v6, v7
	v_add_u32_e32 v6, s24, v12
	v_ashrrev_i32_e32 v7, 31, v6
	s_waitcnt lgkmcnt(0)
	v_cvt_pk_bf16_f32 v5, v8, v9
	v_mul_lo_u32 v8, s16, v7
	v_mul_lo_u32 v9, s17, v6
	v_mad_u64_u32 v[6:7], s[6:7], s16, v6, 0
	v_add3_u32 v7, v7, v8, v9
	v_lshl_add_u64 v[6:7], v[6:7], 1, v[0:1]
	global_store_dwordx4 v[6:7], v[2:5], off
	s_nop 1
	v_add_u32_e32 v2, 0xe00, v68
	v_ashrrev_i32_e32 v12, 4, v2
	v_xor_b32_e32 v2, v12, v10
	v_lshl_add_u32 v8, v2, 2, v11
	ds_read2st64_b32 v[2:3], v8 offset1:4
	ds_read2st64_b32 v[4:5], v8 offset0:8 offset1:12
	ds_read2st64_b32 v[6:7], v8 offset0:16 offset1:20
	ds_read2st64_b32 v[8:9], v8 offset0:24 offset1:28
	s_waitcnt lgkmcnt(3)
	v_cvt_pk_bf16_f32 v2, v2, v3
	s_waitcnt lgkmcnt(2)
	v_cvt_pk_bf16_f32 v3, v4, v5
	s_waitcnt lgkmcnt(1)
	v_cvt_pk_bf16_f32 v4, v6, v7
	v_add_u32_e32 v6, s24, v12
	v_ashrrev_i32_e32 v7, 31, v6
	s_waitcnt lgkmcnt(0)
	v_cvt_pk_bf16_f32 v5, v8, v9
	v_mul_lo_u32 v8, s16, v7
	v_mul_lo_u32 v9, s17, v6
	v_mad_u64_u32 v[6:7], s[6:7], s16, v6, 0
	v_add3_u32 v7, v7, v8, v9
	v_lshl_add_u64 v[0:1], v[6:7], 1, v[0:1]
	global_store_dwordx4 v[0:1], v[2:5], off
	s_barrier
	s_cbranch_scc1 .LBB0_258

; __device__ __forceinline__ int tidx() { int t = threadIdx.x; asm volatile("" : "+v"(t)); return t; }
; #define LAS __attribute__((address_space(3)))
; __device__ __forceinline__ void transpose_tile(const float* src, int ld, int K, const float* gvec, bf16_t* dst, int kt, int nt, int mode, LAS float* tl) {
;     const int tid = tidx(); const int k0 = kt * 128, n0 = nt * 256;
;     f32x4 v[16];
;     const int j = (tid & 63) * 4; const int sc = (mode == 1) ? ((j < 128) ? nt * 128 + j : FF + nt * 128 + j - 128) : n0 + j;
;     const float* sp = src + (size_t)(k0 + (tid >> 6)) * ld + sc;
; #pragma unroll
;     for (int i = 0; i < 16; ++i) v[i] = *(const f32x4*)(sp + (size_t)(8 * i) * ld);
; #pragma unroll
;     for (int i = 0; i < 16; ++i) {
;         const int row = (tid >> 6) + 8 * i;
;         const float g = gvec ? gvec[k0 + row] : 1.f;
;         const int sw = ((row >> 3) & 15) << 1; LAS float* q = tl + row * 256;
;         q[(j) ^ sw] = v[i].x * g; q[(j + 1) ^ sw] = v[i].y * g; q[(j + 2) ^ sw] = v[i].z * g; q[(j + 3) ^ sw] = v[i].w * g;
;     }
.LBB0_225:
	s_lshl_b32 s18, s18, 7
	v_ashrrev_i32_e32 v70, 6, v68
	v_add_u32_e32 v66, s18, v70
	v_mad_u64_u32 v[2:3], s[6:7], v66, s30, 0
	v_ashrrev_i32_e32 v67, 31, v66
	v_mov_b32_e32 v4, v3
	v_mad_u64_u32 v[4:5], s[6:7], v67, s30, v[4:5]
	v_mov_b32_e32 v3, v4
	v_lshl_add_u64 v[2:3], v[2:3], 2, s[20:21]
	v_ashrrev_i32_e32 v1, 31, v0
	v_readlane_b32 s6, v253, 11
	v_lshl_add_u64 v[0:1], v[0:1], 2, v[2:3]
	v_readlane_b32 s7, v253, 12
	s_lshl_b32 s6, s30, 3
	s_mov_b32 s3, s7
	v_lshl_add_u64 v[2:3], s[6:7], 2, v[0:1]
	s_lshl_b32 s6, s30, 4
	global_load_dwordx4 v[60:63], v[0:1], off
	global_load_dwordx4 v[56:59], v[2:3], off
	v_lshl_add_u64 v[2:3], s[6:7], 2, v[0:1]
	s_mul_i32 s6, s30, 24
	v_lshl_add_u64 v[4:5], s[6:7], 2, v[0:1]
	s_lshl_b32 s6, s30, 5
	global_load_dwordx4 v[52:55], v[2:3], off
	global_load_dwordx4 v[48:51], v[4:5], off
	v_lshl_add_u64 v[2:3], s[6:7], 2, v[0:1]
	s_mul_i32 s6, s30, 40
	v_lshl_add_u64 v[4:5], s[6:7], 2, v[0:1]
	s_mul_i32 s6, s30, 48
	global_load_dwordx4 v[44:47], v[2:3], off
	global_load_dwordx4 v[40:43], v[4:5], off
	v_lshl_add_u64 v[2:3], s[6:7], 2, v[0:1]
	s_mul_i32 s6, s30, 56
	v_lshl_add_u64 v[4:5], s[6:7], 2, v[0:1]
	s_lshl_b32 s6, s30, 6
	global_load_dwordx4 v[36:39], v[2:3], off
	global_load_dwordx4 v[32:35], v[4:5], off
	v_lshl_add_u64 v[2:3], s[6:7], 2, v[0:1]
	s_mul_i32 s6, s30, 0x48
	v_lshl_add_u64 v[4:5], s[6:7], 2, v[0:1]
	s_mul_i32 s6, s30, 0x50
	global_load_dwordx4 v[28:31], v[2:3], off
	global_load_dwordx4 v[24:27], v[4:5], off
	v_lshl_add_u64 v[2:3], s[6:7], 2, v[0:1]
	s_mul_i32 s6, s30, 0x58
	v_lshl_add_u64 v[4:5], s[6:7], 2, v[0:1]
	s_mul_i32 s6, s30, 0x60
	global_load_dwordx4 v[20:23], v[2:3], off
	global_load_dwordx4 v[16:19], v[4:5], off
	v_lshl_add_u64 v[2:3], s[6:7], 2, v[0:1]
	s_mul_i32 s6, s30, 0x68
	v_lshl_add_u64 v[4:5], s[6:7], 2, v[0:1]
	s_mul_i32 s6, s30, 0x70
	global_load_dwordx4 v[12:15], v[2:3], off
	global_load_dwordx4 v[8:11], v[4:5], off
	v_lshl_add_u64 v[2:3], s[6:7], 2, v[0:1]
	s_mul_i32 s6, s30, 0x78
	v_lshl_add_u64 v[0:1], s[6:7], 2, v[0:1]
	global_load_dwordx4 v[4:7], v[2:3], off
	s_nop 0
	global_load_dwordx4 v[0:3], v[0:1], off
	v_writelane_b32 v253, s2, 11
	s_cmp_lg_u64 s[22:23], 0
	v_mov_b32_e32 v74, 1.0
	v_writelane_b32 v253, s3, 12
	s_cselect_b64 s[20:21], -1, 0
	s_cmp_eq_u64 s[22:23], 0
	v_lshl_add_u64 v[66:67], v[66:67], 2, s[22:23]
	v_mov_b32_e32 v75, 1.0
	v_mov_b32_e32 v80, 1.0
	v_mov_b32_e32 v81, 1.0
	v_mov_b32_e32 v82, 1.0
	v_mov_b32_e32 v83, 1.0
	v_mov_b32_e32 v84, 1.0
	v_mov_b32_e32 v85, 1.0
	v_mov_b32_e32 v86, 1.0
	v_mov_b32_e32 v87, 1.0
	v_mov_b32_e32 v88, 1.0
	v_mov_b32_e32 v89, 1.0
	v_mov_b32_e32 v90, 1.0
	v_mov_b32_e32 v91, 1.0
	v_mov_b32_e32 v92, 1.0
	v_mov_b32_e32 v93, 1.0
	v_mov_b32_e32 v94, 1.0
	v_mov_b32_e32 v95, 1.0
	s_cbranch_scc1 .LBB0_227
	global_load_dword v80, v[66:67], off
	global_load_dword v81, v[66:67], off offset:32
	global_load_dword v82, v[66:67], off offset:64
	global_load_dword v83, v[66:67], off offset:96
	global_load_dword v84, v[66:67], off offset:128
	global_load_dword v85, v[66:67], off offset:160
	global_load_dword v86, v[66:67], off offset:192
	global_load_dword v87, v[66:67], off offset:224
	global_load_dword v88, v[66:67], off offset:256
	global_load_dword v89, v[66:67], off offset:288
	global_load_dword v90, v[66:67], off offset:320
	global_load_dword v91, v[66:67], off offset:352
	global_load_dword v92, v[66:67], off offset:384
	global_load_dword v93, v[66:67], off offset:416
	global_load_dword v94, v[66:67], off offset:448
	global_load_dword v95, v[66:67], off offset:480
.LBB0_227:
	v_lshrrev_b32_e32 v76, 2, v70
	v_lshl_add_u32 v77, v70, 10, 0
	v_bitop3_b32 v78, v76, v69, 30 bitop3:0x6c
	v_or_b32_e32 v73, 1, v69
	s_waitcnt vmcnt(0)
	v_mul_f32_e32 v60, v60, v80
	v_lshl_add_u32 v78, v78, 2, v77
	ds_write_b32 v78, v60
	v_mul_f32_e32 v60, v61, v80
	v_bitop3_b32 v61, v76, v73, 30 bitop3:0x6c
	v_or_b32_e32 v72, 2, v69
	v_lshl_add_u32 v61, v61, 2, v77
	ds_write_b32 v61, v60
	v_bitop3_b32 v61, v76, v72, 30 bitop3:0x6c
	v_or_b32_e32 v71, 3, v69
	v_mul_f32_e32 v60, v62, v80
	v_lshl_add_u32 v61, v61, 2, v77
	ds_write_b32 v61, v60
	v_bitop3_b32 v61, v76, v71, 30 bitop3:0x6c
	v_cndmask_b32_e64 v62, 0, 1, s[20:21]
	v_mul_f32_e32 v60, v63, v80
	v_lshl_add_u32 v61, v61, 2, v77
	v_cmp_ne_u32_e64 s[6:7], 1, v62
	s_andn2_b64 vcc, exec, s[20:21]
	ds_write_b32 v61, v60
	s_cbranch_vccnz .LBB0_229
.LBB0_229:
	v_add_u32_e32 v60, 8, v70
	v_lshrrev_b32_e32 v61, 2, v60
	v_lshl_add_u32 v60, v60, 10, 0
	v_bitop3_b32 v62, v61, v69, 30 bitop3:0x6c
	s_waitcnt vmcnt(0)
	v_mul_f32_e32 v56, v56, v81
	v_lshl_add_u32 v62, v62, 2, v60
	ds_write_b32 v62, v56
	v_mul_f32_e32 v56, v57, v81
	v_bitop3_b32 v57, v61, v73, 30 bitop3:0x6c
	v_lshl_add_u32 v57, v57, 2, v60
	ds_write_b32 v57, v56
	v_bitop3_b32 v57, v61, v72, 30 bitop3:0x6c
	v_mul_f32_e32 v56, v58, v81
	v_lshl_add_u32 v57, v57, 2, v60
	ds_write_b32 v57, v56
	v_bitop3_b32 v57, v61, v71, 30 bitop3:0x6c
	v_mul_f32_e32 v56, v59, v81
	v_lshl_add_u32 v57, v57, 2, v60
	ds_write_b32 v57, v56
	v_mov_b32_e32 v56, 1.0
	s_and_b64 vcc, exec, s[6:7]
	v_mov_b32_e32 v57, 1.0
	s_cbranch_vccnz .LBB0_231
.LBB0_231:
	v_add_u32_e32 v58, 16, v70
	v_lshrrev_b32_e32 v59, 2, v58
	v_lshl_add_u32 v58, v58, 10, 0
	v_bitop3_b32 v60, v59, v69, 30 bitop3:0x6c
	s_waitcnt vmcnt(0)
	v_mul_f32_e32 v52, v52, v82
	v_lshl_add_u32 v60, v60, 2, v58
	ds_write_b32 v60, v52
	v_mul_f32_e32 v52, v53, v82
	v_bitop3_b32 v53, v59, v73, 30 bitop3:0x6c
	v_lshl_add_u32 v53, v53, 2, v58
	ds_write_b32 v53, v52
	v_bitop3_b32 v53, v59, v72, 30 bitop3:0x6c
	v_mul_f32_e32 v52, v54, v82
	v_lshl_add_u32 v53, v53, 2, v58
	ds_write_b32 v53, v52
	v_bitop3_b32 v53, v59, v71, 30 bitop3:0x6c
	v_mul_f32_e32 v52, v55, v82
	v_lshl_add_u32 v53, v53, 2, v58
	s_and_b64 vcc, exec, s[6:7]
	ds_write_b32 v53, v52
	s_cbranch_vccnz .LBB0_233
; #define LAS __attribute__((address_space(3)))
; __device__ __forceinline__ void transpose_tile(const float* src, int ld, int K, const float* gvec, bf16_t* dst, int kt, int nt, int mode, LAS float* tl) {
;     ...
;     for (int i = 0; i < 16; ++i) {
;         const int row = (tid >> 6) + 8 * i;
;         const float g = gvec ? gvec[k0 + row] : 1.f;
;         const int sw = ((row >> 3) & 15) << 1; LAS float* q = tl + row * 256;
;         q[(j) ^ sw] = v[i].x * g; q[(j + 1) ^ sw] = v[i].y * g; q[(j + 2) ^ sw] = v[i].z * g; q[(j + 3) ^ sw] = v[i].w * g;
;     }
.LBB0_233:
	v_add_u32_e32 v52, 24, v70
	v_lshrrev_b32_e32 v53, 2, v52
	v_lshl_add_u32 v52, v52, 10, 0
	v_bitop3_b32 v54, v53, v69, 30 bitop3:0x6c
	s_waitcnt vmcnt(0)
	v_mul_f32_e32 v48, v48, v83
	v_lshl_add_u32 v54, v54, 2, v52
	ds_write_b32 v54, v48
	v_mul_f32_e32 v48, v49, v83
	v_bitop3_b32 v49, v53, v73, 30 bitop3:0x6c
	v_lshl_add_u32 v49, v49, 2, v52
	ds_write_b32 v49, v48
	v_bitop3_b32 v49, v53, v72, 30 bitop3:0x6c
	v_mul_f32_e32 v48, v50, v83
	v_lshl_add_u32 v49, v49, 2, v52
	ds_write_b32 v49, v48
	v_bitop3_b32 v49, v53, v71, 30 bitop3:0x6c
	v_mul_f32_e32 v48, v51, v83
	v_lshl_add_u32 v49, v49, 2, v52
	ds_write_b32 v49, v48
	v_mov_b32_e32 v48, 1.0
	s_and_b64 vcc, exec, s[6:7]
	v_mov_b32_e32 v49, 1.0
	s_cbranch_vccnz .LBB0_235
.LBB0_235:
	v_add_u32_e32 v50, 32, v70
	v_lshrrev_b32_e32 v51, 2, v50
	v_lshl_add_u32 v50, v50, 10, 0
	v_bitop3_b32 v52, v51, v69, 30 bitop3:0x6c
	s_waitcnt vmcnt(0)
	v_mul_f32_e32 v44, v44, v84
	v_lshl_add_u32 v52, v52, 2, v50
	ds_write_b32 v52, v44
	v_mul_f32_e32 v44, v45, v84
	v_bitop3_b32 v45, v51, v73, 30 bitop3:0x6c
	v_lshl_add_u32 v45, v45, 2, v50
	ds_write_b32 v45, v44
	v_bitop3_b32 v45, v51, v72, 30 bitop3:0x6c
	v_mul_f32_e32 v44, v46, v84
	v_lshl_add_u32 v45, v45, 2, v50
	ds_write_b32 v45, v44
	v_bitop3_b32 v45, v51, v71, 30 bitop3:0x6c
	v_mul_f32_e32 v44, v47, v84
	v_lshl_add_u32 v45, v45, 2, v50
	s_and_b64 vcc, exec, s[6:7]
	ds_write_b32 v45, v44
	s_cbranch_vccnz .LBB0_237
.LBB0_237:
	v_add_u32_e32 v44, 40, v70
	v_lshrrev_b32_e32 v45, 2, v44
	v_lshl_add_u32 v44, v44, 10, 0
	v_bitop3_b32 v46, v45, v69, 30 bitop3:0x6c
	s_waitcnt vmcnt(0)
	v_mul_f32_e32 v40, v40, v85
	v_lshl_add_u32 v46, v46, 2, v44
	ds_write_b32 v46, v40
	v_mul_f32_e32 v40, v41, v85
	v_bitop3_b32 v41, v45, v73, 30 bitop3:0x6c
	v_lshl_add_u32 v41, v41, 2, v44
	ds_write_b32 v41, v40
	v_bitop3_b32 v41, v45, v72, 30 bitop3:0x6c
	v_mul_f32_e32 v40, v42, v85
	v_lshl_add_u32 v41, v41, 2, v44
	ds_write_b32 v41, v40
	v_bitop3_b32 v41, v45, v71, 30 bitop3:0x6c
	v_mul_f32_e32 v40, v43, v85
	v_lshl_add_u32 v41, v41, 2, v44
	ds_write_b32 v41, v40
	v_mov_b32_e32 v40, 1.0
	s_and_b64 vcc, exec, s[6:7]
	v_mov_b32_e32 v41, 1.0
	s_cbranch_vccnz .LBB0_239
.LBB0_239:
	v_add_u32_e32 v42, 48, v70
	v_lshrrev_b32_e32 v43, 2, v42
	v_lshl_add_u32 v42, v42, 10, 0
	v_bitop3_b32 v44, v43, v69, 30 bitop3:0x6c
	s_waitcnt vmcnt(0)
	v_mul_f32_e32 v36, v36, v86
	v_lshl_add_u32 v44, v44, 2, v42
	ds_write_b32 v44, v36
	v_mul_f32_e32 v36, v37, v86
	v_bitop3_b32 v37, v43, v73, 30 bitop3:0x6c
	v_lshl_add_u32 v37, v37, 2, v42
	ds_write_b32 v37, v36
	v_bitop3_b32 v37, v43, v72, 30 bitop3:0x6c
	v_mul_f32_e32 v36, v38, v86
	v_lshl_add_u32 v37, v37, 2, v42
	ds_write_b32 v37, v36
	v_bitop3_b32 v37, v43, v71, 30 bitop3:0x6c
	v_mul_f32_e32 v36, v39, v86
	v_lshl_add_u32 v37, v37, 2, v42
	s_and_b64 vcc, exec, s[6:7]
	ds_write_b32 v37, v36
	s_cbranch_vccnz .LBB0_241
.LBB0_241:
	v_add_u32_e32 v36, 56, v70
	v_lshrrev_b32_e32 v37, 2, v36
	v_lshl_add_u32 v36, v36, 10, 0
	v_bitop3_b32 v38, v37, v69, 30 bitop3:0x6c
	s_waitcnt vmcnt(0)
	v_mul_f32_e32 v32, v32, v87
	v_lshl_add_u32 v38, v38, 2, v36
	ds_write_b32 v38, v32
	v_mul_f32_e32 v32, v33, v87
	v_bitop3_b32 v33, v37, v73, 30 bitop3:0x6c
	v_lshl_add_u32 v33, v33, 2, v36
	ds_write_b32 v33, v32
	v_bitop3_b32 v33, v37, v72, 30 bitop3:0x6c
	v_mul_f32_e32 v32, v34, v87
	v_lshl_add_u32 v33, v33, 2, v36
	ds_write_b32 v33, v32
	v_bitop3_b32 v33, v37, v71, 30 bitop3:0x6c
	v_mul_f32_e32 v32, v35, v87
	v_lshl_add_u32 v33, v33, 2, v36
	ds_write_b32 v33, v32
	v_mov_b32_e32 v32, 1.0
	s_and_b64 vcc, exec, s[6:7]
	v_mov_b32_e32 v33, 1.0
	s_cbranch_vccnz .LBB0_243
.LBB0_243:
	v_add_u32_e32 v34, 64, v70
	v_lshrrev_b32_e32 v35, 2, v34
	v_lshl_add_u32 v34, v34, 10, 0
	v_bitop3_b32 v36, v35, v69, 30 bitop3:0x6c
	s_waitcnt vmcnt(0)
	v_mul_f32_e32 v28, v28, v88
	v_lshl_add_u32 v36, v36, 2, v34
	ds_write_b32 v36, v28
	v_mul_f32_e32 v28, v29, v88
	v_bitop3_b32 v29, v35, v73, 30 bitop3:0x6c
	v_lshl_add_u32 v29, v29, 2, v34
	ds_write_b32 v29, v28
	v_bitop3_b32 v29, v35, v72, 30 bitop3:0x6c
	v_mul_f32_e32 v28, v30, v88
	v_lshl_add_u32 v29, v29, 2, v34
	ds_write_b32 v29, v28
	v_bitop3_b32 v29, v35, v71, 30 bitop3:0x6c
	v_mul_f32_e32 v28, v31, v88
	v_lshl_add_u32 v29, v29, 2, v34
	s_and_b64 vcc, exec, s[6:7]
	ds_write_b32 v29, v28
	s_cbranch_vccnz .LBB0_245
; #define LAS __attribute__((address_space(3)))
; __device__ __forceinline__ void transpose_tile(const float* src, int ld, int K, const float* gvec, bf16_t* dst, int kt, int nt, int mode, LAS float* tl) {
;     ...
;     for (int i = 0; i < 16; ++i) {
;         const int row = (tid >> 6) + 8 * i;
;         const float g = gvec ? gvec[k0 + row] : 1.f;
;         const int sw = ((row >> 3) & 15) << 1; LAS float* q = tl + row * 256;
;         q[(j) ^ sw] = v[i].x * g; q[(j + 1) ^ sw] = v[i].y * g; q[(j + 2) ^ sw] = v[i].z * g; q[(j + 3) ^ sw] = v[i].w * g;
;     }
.LBB0_245:
	v_add_u32_e32 v28, 0x48, v70
	v_lshrrev_b32_e32 v29, 2, v28
	v_lshl_add_u32 v28, v28, 10, 0
	v_bitop3_b32 v30, v29, v69, 30 bitop3:0x6c
	s_waitcnt vmcnt(0)
	v_mul_f32_e32 v24, v24, v89
	v_lshl_add_u32 v30, v30, 2, v28
	ds_write_b32 v30, v24
	v_mul_f32_e32 v24, v25, v89
	v_bitop3_b32 v25, v29, v73, 30 bitop3:0x6c
	v_lshl_add_u32 v25, v25, 2, v28
	ds_write_b32 v25, v24
	v_bitop3_b32 v25, v29, v72, 30 bitop3:0x6c
	v_mul_f32_e32 v24, v26, v89
	v_lshl_add_u32 v25, v25, 2, v28
	ds_write_b32 v25, v24
	v_bitop3_b32 v25, v29, v71, 30 bitop3:0x6c
	v_mul_f32_e32 v24, v27, v89
	v_lshl_add_u32 v25, v25, 2, v28
	ds_write_b32 v25, v24
	v_mov_b32_e32 v24, 1.0
	s_and_b64 vcc, exec, s[6:7]
	v_mov_b32_e32 v25, 1.0
	s_cbranch_vccnz .LBB0_247
.LBB0_247:
	v_add_u32_e32 v26, 0x50, v70
	v_lshrrev_b32_e32 v27, 2, v26
	v_lshl_add_u32 v26, v26, 10, 0
	v_bitop3_b32 v28, v27, v69, 30 bitop3:0x6c
	s_waitcnt vmcnt(0)
	v_mul_f32_e32 v20, v20, v90
	v_lshl_add_u32 v28, v28, 2, v26
	ds_write_b32 v28, v20
	v_mul_f32_e32 v20, v21, v90
	v_bitop3_b32 v21, v27, v73, 30 bitop3:0x6c
	v_lshl_add_u32 v21, v21, 2, v26
	ds_write_b32 v21, v20
	v_bitop3_b32 v21, v27, v72, 30 bitop3:0x6c
	v_mul_f32_e32 v20, v22, v90
	v_lshl_add_u32 v21, v21, 2, v26
	ds_write_b32 v21, v20
	v_bitop3_b32 v21, v27, v71, 30 bitop3:0x6c
	v_mul_f32_e32 v20, v23, v90
	v_lshl_add_u32 v21, v21, 2, v26
	s_and_b64 vcc, exec, s[6:7]
	ds_write_b32 v21, v20
	s_cbranch_vccnz .LBB0_249
.LBB0_249:
	v_add_u32_e32 v20, 0x58, v70
	v_lshrrev_b32_e32 v21, 2, v20
	v_lshl_add_u32 v20, v20, 10, 0
	v_bitop3_b32 v22, v21, v69, 30 bitop3:0x6c
	s_waitcnt vmcnt(0)
	v_mul_f32_e32 v16, v16, v91
	v_lshl_add_u32 v22, v22, 2, v20
	ds_write_b32 v22, v16
	v_mul_f32_e32 v16, v17, v91
	v_bitop3_b32 v17, v21, v73, 30 bitop3:0x6c
	v_lshl_add_u32 v17, v17, 2, v20
	ds_write_b32 v17, v16
	v_bitop3_b32 v17, v21, v72, 30 bitop3:0x6c
	v_mul_f32_e32 v16, v18, v91
	v_lshl_add_u32 v17, v17, 2, v20
	ds_write_b32 v17, v16
	v_bitop3_b32 v17, v21, v71, 30 bitop3:0x6c
	v_mul_f32_e32 v16, v19, v91
	v_lshl_add_u32 v17, v17, 2, v20
	ds_write_b32 v17, v16
	v_mov_b32_e32 v16, 1.0
	s_and_b64 vcc, exec, s[6:7]
	v_mov_b32_e32 v17, 1.0
	s_cbranch_vccnz .LBB0_251
.LBB0_251:
	v_add_u32_e32 v18, 0x60, v70
	v_lshrrev_b32_e32 v19, 2, v18
	v_lshl_add_u32 v18, v18, 10, 0
	v_bitop3_b32 v20, v19, v69, 30 bitop3:0x6c
	s_waitcnt vmcnt(0)
	v_mul_f32_e32 v12, v12, v92
	v_lshl_add_u32 v20, v20, 2, v18
	ds_write_b32 v20, v12
	v_mul_f32_e32 v12, v13, v92
	v_bitop3_b32 v13, v19, v73, 30 bitop3:0x6c
	v_lshl_add_u32 v13, v13, 2, v18
	ds_write_b32 v13, v12
	v_bitop3_b32 v13, v19, v72, 30 bitop3:0x6c
	v_mul_f32_e32 v12, v14, v92
	v_lshl_add_u32 v13, v13, 2, v18
	ds_write_b32 v13, v12
	v_bitop3_b32 v13, v19, v71, 30 bitop3:0x6c
	v_mul_f32_e32 v12, v15, v92
	v_lshl_add_u32 v13, v13, 2, v18
	s_and_b64 vcc, exec, s[6:7]
	ds_write_b32 v13, v12
	s_cbranch_vccnz .LBB0_253
.LBB0_253:
	v_add_u32_e32 v12, 0x68, v70
	v_lshrrev_b32_e32 v13, 2, v12
	v_lshl_add_u32 v12, v12, 10, 0
	v_bitop3_b32 v14, v13, v69, 30 bitop3:0x6c
	s_waitcnt vmcnt(0)
	v_mul_f32_e32 v8, v8, v93
	v_lshl_add_u32 v14, v14, 2, v12
	ds_write_b32 v14, v8
	v_mul_f32_e32 v8, v9, v93
	v_bitop3_b32 v9, v13, v73, 30 bitop3:0x6c
	v_lshl_add_u32 v9, v9, 2, v12
	ds_write_b32 v9, v8
	v_bitop3_b32 v9, v13, v72, 30 bitop3:0x6c
	v_mul_f32_e32 v8, v10, v93
	v_lshl_add_u32 v9, v9, 2, v12
	ds_write_b32 v9, v8
	v_bitop3_b32 v9, v13, v71, 30 bitop3:0x6c
	v_mul_f32_e32 v8, v11, v93
	v_lshl_add_u32 v9, v9, 2, v12
	ds_write_b32 v9, v8
	v_mov_b32_e32 v8, 1.0
	s_and_b64 vcc, exec, s[6:7]
	v_mov_b32_e32 v9, 1.0
	s_cbranch_vccnz .LBB0_255
.LBB0_255:
	v_add_u32_e32 v10, 0x70, v70
	v_lshrrev_b32_e32 v11, 2, v10
	v_lshl_add_u32 v10, v10, 10, 0
	v_bitop3_b32 v12, v11, v69, 30 bitop3:0x6c
	s_waitcnt vmcnt(0)
	v_mul_f32_e32 v4, v4, v94
	v_lshl_add_u32 v12, v12, 2, v10
	ds_write_b32 v12, v4
	v_mul_f32_e32 v4, v5, v94
	v_bitop3_b32 v5, v11, v73, 30 bitop3:0x6c
	v_lshl_add_u32 v5, v5, 2, v10
	ds_write_b32 v5, v4
	v_bitop3_b32 v5, v11, v72, 30 bitop3:0x6c
	v_mul_f32_e32 v4, v6, v94
	v_lshl_add_u32 v5, v5, 2, v10
	ds_write_b32 v5, v4
	v_bitop3_b32 v5, v11, v71, 30 bitop3:0x6c
	v_mul_f32_e32 v4, v7, v94
	v_lshl_add_u32 v5, v5, 2, v10
	s_and_b64 vcc, exec, s[6:7]
	ds_write_b32 v5, v4
	s_cbranch_vccnz .LBB0_202
	s_branch .LBB0_202

; #define LAS __attribute__((address_space(3)))
; __device__ __forceinline__ void transpose_tile(const float* src, int ld, int K, const float* gvec, bf16_t* dst, int kt, int nt, int mode, LAS float* tl) {
;     ...
;     for (int i = 0; i < 16; ++i) {
;         const int row = (tid >> 6) + 8 * i;
;         const float g = gvec ? gvec[k0 + row] : 1.f;
;         const int sw = ((row >> 3) & 15) << 1; LAS float* q = tl + row * 256;
;         q[(j) ^ sw] = v[i].x * g; q[(j + 1) ^ sw] = v[i].y * g; q[(j + 2) ^ sw] = v[i].z * g; q[(j + 3) ^ sw] = v[i].w * g;
;     }
.LBB0_739:
	v_add_u32_e32 v4, 0x78, v71
	v_lshrrev_b32_e32 v5, 2, v4
	v_lshl_add_u32 v4, v4, 10, 0
	v_bitop3_b32 v6, v5, v70, 30 bitop3:0x6c
	s_waitcnt vmcnt(0)
	v_mul_f32_e32 v0, v0, v95
	v_lshl_add_u32 v6, v6, 2, v4
	ds_write_b32 v6, v0
	v_mul_f32_e32 v0, v1, v95
	v_bitop3_b32 v1, v5, v74, 30 bitop3:0x6c
	v_lshl_add_u32 v1, v1, 2, v4
	ds_write_b32 v1, v0
	v_mul_f32_e32 v0, v2, v95
	v_bitop3_b32 v1, v5, v73, 30 bitop3:0x6c
	v_and_b32_e32 v2, 15, v65
	v_lshl_add_u32 v1, v1, 2, v4
	v_lshlrev_b32_e32 v16, 1, v2
	v_ashrrev_i32_e32 v10, 4, v65
	ds_write_b32 v1, v0
	v_bitop3_b32 v1, v5, v72, 30 bitop3:0x6c
	v_lshl_add_u32 v17, v2, 13, 0
	v_lshlrev_b32_e32 v136, 4, v2
	v_xor_b32_e32 v2, v16, v10
	v_mul_f32_e32 v0, v3, v95
	v_lshl_add_u32 v1, v1, 2, v4
	v_lshl_add_u32 v8, v2, 2, v17
	ds_write_b32 v1, v0
	s_waitcnt lgkmcnt(0)
	s_barrier
; __device__ __forceinline__ unsigned cvt_pk_bf16(float lo, float hi) { unsigned r; asm volatile("v_cvt_pk_bf16_f32 %0, %1, %2" : "=v"(r) : "v"(lo), "v"(hi)); return r; }
; __device__ __forceinline__ void transpose_tile(const float* src, int ld, int K, const float* gvec, bf16_t* dst, int kt, int nt, int mode, LAS float* tl) {
;     ...
;     __syncthreads();
; #pragma unroll
;     for (int jj = 0; jj < 8; ++jj) {
;         const int c = tid + 512 * jj; const int n = c >> 4, kc = c & 15;
;         float x[8];
; #pragma unroll
;         for (int i = 0; i < 8; ++i) x[i] = tl[(kc * 8 + i) * 256 + (n ^ (kc << 1))];
;         u32x4 w; w.x = cvt_pk_bf16(x[0], x[1]); w.y = cvt_pk_bf16(x[2], x[3]); w.z = cvt_pk_bf16(x[4], x[5]); w.w = cvt_pk_bf16(x[6], x[7]);
;         *(u32x4*)(dst + (size_t)(n0 + n) * K + k0 + kc * 8) = w;
;     }
	ds_read2st64_b32 v[2:3], v8 offset1:4
	ds_read2st64_b32 v[4:5], v8 offset0:8 offset1:12
	ds_read2st64_b32 v[6:7], v8 offset0:16 offset1:20
	ds_read2st64_b32 v[8:9], v8 offset0:24 offset1:28
	s_ashr_i32 s5, s4, 31
	s_waitcnt lgkmcnt(3)
	v_cvt_pk_bf16_f32 v2, v2, v3
	s_waitcnt lgkmcnt(2)
	v_cvt_pk_bf16_f32 v3, v4, v5
	s_waitcnt lgkmcnt(1)
	v_cvt_pk_bf16_f32 v4, v6, v7
	v_add_u32_e32 v6, s12, v10
	s_lshl_b64 s[4:5], s[4:5], 1
	v_ashrrev_i32_e32 v7, 31, v6
	v_lshl_add_u64 v[0:1], v[66:67], 0, s[4:5]
	s_waitcnt lgkmcnt(0)
	v_cvt_pk_bf16_f32 v5, v8, v9
	v_mul_lo_u32 v8, s0, v7
	v_mul_lo_u32 v9, s1, v6
	v_mad_u64_u32 v[6:7], s[4:5], s0, v6, 0
	v_add3_u32 v7, v7, v8, v9
	v_add_u32_e32 v8, 0x200, v65
	v_ashrrev_i32_e32 v18, 4, v8
	v_lshl_add_u64 v[0:1], v[0:1], 0, v[136:137]
	v_xor_b32_e32 v8, v18, v16
	v_lshl_add_u64 v[6:7], v[6:7], 1, v[0:1]
	v_lshl_add_u32 v14, v8, 2, v17
	ds_read2st64_b32 v[8:9], v14 offset1:4
	ds_read2st64_b32 v[10:11], v14 offset0:8 offset1:12
	ds_read2st64_b32 v[12:13], v14 offset0:16 offset1:20
	ds_read2st64_b32 v[14:15], v14 offset0:24 offset1:28
	global_store_dwordx4 v[6:7], v[2:5], off
	v_add_u32_e32 v6, s12, v18
	v_ashrrev_i32_e32 v7, 31, v6
	s_waitcnt lgkmcnt(3)
	v_cvt_pk_bf16_f32 v2, v8, v9
	v_mul_lo_u32 v8, s0, v7
	v_mul_lo_u32 v9, s1, v6
	v_mad_u64_u32 v[6:7], s[4:5], s0, v6, 0
	v_add3_u32 v7, v7, v8, v9
	v_add_u32_e32 v8, 0x400, v65
	v_ashrrev_i32_e32 v18, 4, v8
	v_xor_b32_e32 v8, v18, v16
	s_waitcnt lgkmcnt(2)
	v_cvt_pk_bf16_f32 v3, v10, v11
	s_waitcnt lgkmcnt(1)
	v_cvt_pk_bf16_f32 v4, v12, v13
	s_waitcnt lgkmcnt(0)
	v_cvt_pk_bf16_f32 v5, v14, v15
	v_lshl_add_u64 v[6:7], v[6:7], 1, v[0:1]
	v_lshl_add_u32 v14, v8, 2, v17
	ds_read2st64_b32 v[8:9], v14 offset1:4
	ds_read2st64_b32 v[10:11], v14 offset0:8 offset1:12
	ds_read2st64_b32 v[12:13], v14 offset0:16 offset1:20
	ds_read2st64_b32 v[14:15], v14 offset0:24 offset1:28
	global_store_dwordx4 v[6:7], v[2:5], off
	v_add_u32_e32 v6, s12, v18
	v_ashrrev_i32_e32 v7, 31, v6
	s_waitcnt lgkmcnt(3)
	v_cvt_pk_bf16_f32 v2, v8, v9
	v_mul_lo_u32 v8, s0, v7
	v_mul_lo_u32 v9, s1, v6
	v_mad_u64_u32 v[6:7], s[4:5], s0, v6, 0
	v_add3_u32 v7, v7, v8, v9
	v_add_u32_e32 v8, 0x600, v65
	v_ashrrev_i32_e32 v18, 4, v8
	v_xor_b32_e32 v8, v18, v16
	s_waitcnt lgkmcnt(2)
	v_cvt_pk_bf16_f32 v3, v10, v11
	s_waitcnt lgkmcnt(1)
	v_cvt_pk_bf16_f32 v4, v12, v13
	s_waitcnt lgkmcnt(0)
	v_cvt_pk_bf16_f32 v5, v14, v15
	v_lshl_add_u64 v[6:7], v[6:7], 1, v[0:1]
	v_lshl_add_u32 v14, v8, 2, v17
	ds_read2st64_b32 v[8:9], v14 offset1:4
	ds_read2st64_b32 v[10:11], v14 offset0:8 offset1:12
	ds_read2st64_b32 v[12:13], v14 offset0:16 offset1:20
	ds_read2st64_b32 v[14:15], v14 offset0:24 offset1:28
	global_store_dwordx4 v[6:7], v[2:5], off
	v_add_u32_e32 v6, s12, v18
	v_ashrrev_i32_e32 v7, 31, v6
	s_waitcnt lgkmcnt(3)
	v_cvt_pk_bf16_f32 v2, v8, v9
	v_mul_lo_u32 v8, s0, v7
	v_mul_lo_u32 v9, s1, v6
	v_mad_u64_u32 v[6:7], s[4:5], s0, v6, 0
	v_add3_u32 v7, v7, v8, v9
	v_add_u32_e32 v8, 0x800, v65
	v_ashrrev_i32_e32 v18, 4, v8
	v_xor_b32_e32 v8, v18, v16
	s_waitcnt lgkmcnt(2)
	v_cvt_pk_bf16_f32 v3, v10, v11
	s_waitcnt lgkmcnt(1)
	v_cvt_pk_bf16_f32 v4, v12, v13
	s_waitcnt lgkmcnt(0)
	v_cvt_pk_bf16_f32 v5, v14, v15
	v_lshl_add_u64 v[6:7], v[6:7], 1, v[0:1]
	v_lshl_add_u32 v14, v8, 2, v17
	ds_read2st64_b32 v[8:9], v14 offset1:4
	ds_read2st64_b32 v[10:11], v14 offset0:8 offset1:12
	ds_read2st64_b32 v[12:13], v14 offset0:16 offset1:20
	ds_read2st64_b32 v[14:15], v14 offset0:24 offset1:28
	global_store_dwordx4 v[6:7], v[2:5], off
	v_add_u32_e32 v6, s12, v18
	v_ashrrev_i32_e32 v7, 31, v6
	s_waitcnt lgkmcnt(3)
	v_cvt_pk_bf16_f32 v2, v8, v9
	v_mul_lo_u32 v8, s0, v7
	v_mul_lo_u32 v9, s1, v6
	v_mad_u64_u32 v[6:7], s[4:5], s0, v6, 0
	v_add3_u32 v7, v7, v8, v9
	v_add_u32_e32 v8, 0xa00, v65
	v_ashrrev_i32_e32 v18, 4, v8
	v_xor_b32_e32 v8, v18, v16
	s_waitcnt lgkmcnt(2)
	v_cvt_pk_bf16_f32 v3, v10, v11
	s_waitcnt lgkmcnt(1)
	v_cvt_pk_bf16_f32 v4, v12, v13
	s_waitcnt lgkmcnt(0)
	v_cvt_pk_bf16_f32 v5, v14, v15
	v_lshl_add_u64 v[6:7], v[6:7], 1, v[0:1]
	v_lshl_add_u32 v14, v8, 2, v17
	ds_read2st64_b32 v[8:9], v14 offset1:4
	ds_read2st64_b32 v[10:11], v14 offset0:8 offset1:12
	ds_read2st64_b32 v[12:13], v14 offset0:16 offset1:20
	ds_read2st64_b32 v[14:15], v14 offset0:24 offset1:28
	global_store_dwordx4 v[6:7], v[2:5], off
	v_add_u32_e32 v6, s12, v18
	v_ashrrev_i32_e32 v7, 31, v6
	s_waitcnt lgkmcnt(3)
	v_cvt_pk_bf16_f32 v2, v8, v9
	v_mul_lo_u32 v8, s0, v7
	v_mul_lo_u32 v9, s1, v6
	v_mad_u64_u32 v[6:7], s[4:5], s0, v6, 0
	v_add3_u32 v7, v7, v8, v9
	v_add_u32_e32 v8, 0xc00, v65
	v_ashrrev_i32_e32 v18, 4, v8
	v_xor_b32_e32 v8, v18, v16
	s_waitcnt lgkmcnt(2)
	v_cvt_pk_bf16_f32 v3, v10, v11
	s_waitcnt lgkmcnt(1)
	v_cvt_pk_bf16_f32 v4, v12, v13
	s_waitcnt lgkmcnt(0)
	v_cvt_pk_bf16_f32 v5, v14, v15
	v_lshl_add_u64 v[6:7], v[6:7], 1, v[0:1]
	v_lshl_add_u32 v14, v8, 2, v17
	ds_read2st64_b32 v[8:9], v14 offset1:4
	ds_read2st64_b32 v[10:11], v14 offset0:8 offset1:12
	ds_read2st64_b32 v[12:13], v14 offset0:16 offset1:20
	ds_read2st64_b32 v[14:15], v14 offset0:24 offset1:28
	global_store_dwordx4 v[6:7], v[2:5], off
	v_add_u32_e32 v6, s12, v18
	v_ashrrev_i32_e32 v7, 31, v6
	s_waitcnt lgkmcnt(3)
	v_cvt_pk_bf16_f32 v2, v8, v9
	v_mul_lo_u32 v8, s0, v7
	v_mul_lo_u32 v9, s1, v6
	v_mad_u64_u32 v[6:7], s[4:5], s0, v6, 0
	v_add3_u32 v7, v7, v8, v9
	v_add_u32_e32 v8, 0xe00, v65
	v_ashrrev_i32_e32 v18, 4, v8
	v_xor_b32_e32 v8, v18, v16
	s_waitcnt lgkmcnt(2)
	v_cvt_pk_bf16_f32 v3, v10, v11
	s_waitcnt lgkmcnt(1)
	v_cvt_pk_bf16_f32 v4, v12, v13
	s_waitcnt lgkmcnt(0)
	v_cvt_pk_bf16_f32 v5, v14, v15
	v_lshl_add_u64 v[6:7], v[6:7], 1, v[0:1]
	v_lshl_add_u32 v14, v8, 2, v17
	ds_read2st64_b32 v[8:9], v14 offset1:4
	ds_read2st64_b32 v[10:11], v14 offset0:8 offset1:12
	ds_read2st64_b32 v[12:13], v14 offset0:16 offset1:20
	ds_read2st64_b32 v[14:15], v14 offset0:24 offset1:28
	global_store_dwordx4 v[6:7], v[2:5], off
	v_add_u32_e32 v6, s12, v18
	v_ashrrev_i32_e32 v7, 31, v6
	s_waitcnt lgkmcnt(3)
	v_cvt_pk_bf16_f32 v2, v8, v9
	v_mul_lo_u32 v8, s0, v7
	v_mul_lo_u32 v9, s1, v6
	v_mad_u64_u32 v[6:7], s[0:1], s0, v6, 0
	v_readlane_b32 s0, v253, 5
	v_add3_u32 v7, v7, v8, v9
	s_add_i32 s16, s16, s0
	v_lshl_add_u64 v[0:1], v[6:7], 1, v[0:1]
	s_cmpk_gt_i32 s16, 0xe6f
	s_waitcnt lgkmcnt(2)
	v_cvt_pk_bf16_f32 v3, v10, v11
	s_waitcnt lgkmcnt(1)
	v_cvt_pk_bf16_f32 v4, v12, v13
	s_waitcnt lgkmcnt(0)
	v_cvt_pk_bf16_f32 v5, v14, v15
	global_store_dwordx4 v[0:1], v[2:5], off
	s_barrier
	v_readlane_b32 s1, v253, 6
	s_cbranch_scc1 .LBB0_735

; __device__ __forceinline__ int tidx() { int t = threadIdx.x; asm volatile("" : "+v"(t)); return t; }
; #define LAS __attribute__((address_space(3)))
; __device__ __forceinline__ void transpose_tile(const float* src, int ld, int K, const float* gvec, bf16_t* dst, int kt, int nt, int mode, LAS float* tl) {
;     const int tid = tidx(); const int k0 = kt * 128, n0 = nt * 256;
;     f32x4 v[16];
;     const int j = (tid & 63) * 4; const int sc = (mode == 1) ? ((j < 128) ? nt * 128 + j : FF + nt * 128 + j - 128) : n0 + j;
;     const float* sp = src + (size_t)(k0 + (tid >> 6)) * ld + sc;
; #pragma unroll
;     for (int i = 0; i < 16; ++i) v[i] = *(const f32x4*)(sp + (size_t)(8 * i) * ld);
; #pragma unroll
;     for (int i = 0; i < 16; ++i) {
;         const int row = (tid >> 6) + 8 * i;
;         const float g = gvec ? gvec[k0 + row] : 1.f;
;         const int sw = ((row >> 3) & 15) << 1; LAS float* q = tl + row * 256;
;         q[(j) ^ sw] = v[i].x * g; q[(j + 1) ^ sw] = v[i].y * g; q[(j + 2) ^ sw] = v[i].z * g; q[(j + 3) ^ sw] = v[i].w * g;
;     }
.LBB0_762:
	s_lshl_b32 s4, s10, 7
	v_ashrrev_i32_e32 v71, 6, v65
	v_add_u32_e32 v68, s4, v71
	v_mad_u64_u32 v[2:3], s[10:11], v68, s18, 0
	v_ashrrev_i32_e32 v69, 31, v68
	v_mov_b32_e32 v4, v3
	v_mad_u64_u32 v[4:5], s[10:11], v69, s18, v[4:5]
	v_mov_b32_e32 v3, v4
	s_waitcnt lgkmcnt(0)
	v_lshl_add_u64 v[2:3], v[2:3], 2, s[6:7]
	v_ashrrev_i32_e32 v1, 31, v0
	v_readlane_b32 s6, v253, 11
	v_lshl_add_u64 v[0:1], v[0:1], 2, v[2:3]
	v_readlane_b32 s7, v253, 12
	s_lshl_b32 s6, s18, 3
	s_mov_b32 s3, s7
	v_lshl_add_u64 v[2:3], s[6:7], 2, v[0:1]
	s_lshl_b32 s6, s18, 4
	global_load_dwordx4 v[60:63], v[0:1], off
	global_load_dwordx4 v[56:59], v[2:3], off
	v_lshl_add_u64 v[2:3], s[6:7], 2, v[0:1]
	s_mul_i32 s6, s18, 24
	v_lshl_add_u64 v[4:5], s[6:7], 2, v[0:1]
	s_lshl_b32 s6, s18, 5
	global_load_dwordx4 v[52:55], v[2:3], off
	global_load_dwordx4 v[48:51], v[4:5], off
	v_lshl_add_u64 v[2:3], s[6:7], 2, v[0:1]
	s_mul_i32 s6, s18, 40
	v_lshl_add_u64 v[4:5], s[6:7], 2, v[0:1]
	s_mul_i32 s6, s18, 48
	global_load_dwordx4 v[44:47], v[2:3], off
	global_load_dwordx4 v[40:43], v[4:5], off
	v_lshl_add_u64 v[2:3], s[6:7], 2, v[0:1]
	s_mul_i32 s6, s18, 56
	v_lshl_add_u64 v[4:5], s[6:7], 2, v[0:1]
	s_lshl_b32 s6, s18, 6
	global_load_dwordx4 v[36:39], v[2:3], off
	global_load_dwordx4 v[32:35], v[4:5], off
	v_lshl_add_u64 v[2:3], s[6:7], 2, v[0:1]
	s_mul_i32 s6, s18, 0x48
	v_lshl_add_u64 v[4:5], s[6:7], 2, v[0:1]
	s_mul_i32 s6, s18, 0x50
	global_load_dwordx4 v[28:31], v[2:3], off
	global_load_dwordx4 v[24:27], v[4:5], off
	v_lshl_add_u64 v[2:3], s[6:7], 2, v[0:1]
	s_mul_i32 s6, s18, 0x58
	v_lshl_add_u64 v[4:5], s[6:7], 2, v[0:1]
	s_mul_i32 s6, s18, 0x60
	global_load_dwordx4 v[20:23], v[2:3], off
	global_load_dwordx4 v[16:19], v[4:5], off
	v_lshl_add_u64 v[2:3], s[6:7], 2, v[0:1]
	s_mul_i32 s6, s18, 0x68
	v_lshl_add_u64 v[4:5], s[6:7], 2, v[0:1]
	s_mul_i32 s6, s18, 0x70
	global_load_dwordx4 v[12:15], v[2:3], off
	global_load_dwordx4 v[8:11], v[4:5], off
	v_lshl_add_u64 v[2:3], s[6:7], 2, v[0:1]
	s_mul_i32 s6, s18, 0x78
	v_lshl_add_u64 v[0:1], s[6:7], 2, v[0:1]
	global_load_dwordx4 v[4:7], v[2:3], off
	s_nop 0
	global_load_dwordx4 v[0:3], v[0:1], off
	v_writelane_b32 v253, s2, 11
	s_cmp_lg_u64 s[8:9], 0
	v_mov_b32_e32 v75, 1.0
	v_writelane_b32 v253, s3, 12
	s_cselect_b64 s[10:11], -1, 0
	s_cmp_eq_u64 s[8:9], 0
	v_lshl_add_u64 v[68:69], v[68:69], 2, s[8:9]
	v_mov_b32_e32 v76, 1.0
	v_mov_b32_e32 v80, 1.0
	v_mov_b32_e32 v81, 1.0
	v_mov_b32_e32 v82, 1.0
	v_mov_b32_e32 v83, 1.0
	v_mov_b32_e32 v84, 1.0
	v_mov_b32_e32 v85, 1.0
	v_mov_b32_e32 v86, 1.0
	v_mov_b32_e32 v87, 1.0
	v_mov_b32_e32 v88, 1.0
	v_mov_b32_e32 v89, 1.0
	v_mov_b32_e32 v90, 1.0
	v_mov_b32_e32 v91, 1.0
	v_mov_b32_e32 v92, 1.0
	v_mov_b32_e32 v93, 1.0
	v_mov_b32_e32 v94, 1.0
	v_mov_b32_e32 v95, 1.0
	s_cbranch_scc1 .LBB0_764
	global_load_dword v80, v[68:69], off
	global_load_dword v81, v[68:69], off offset:32
	global_load_dword v82, v[68:69], off offset:64
	global_load_dword v83, v[68:69], off offset:96
	global_load_dword v84, v[68:69], off offset:128
	global_load_dword v85, v[68:69], off offset:160
	global_load_dword v86, v[68:69], off offset:192
	global_load_dword v87, v[68:69], off offset:224
	global_load_dword v88, v[68:69], off offset:256
	global_load_dword v89, v[68:69], off offset:288
	global_load_dword v90, v[68:69], off offset:320
	global_load_dword v91, v[68:69], off offset:352
	global_load_dword v92, v[68:69], off offset:384
	global_load_dword v93, v[68:69], off offset:416
	global_load_dword v94, v[68:69], off offset:448
	global_load_dword v95, v[68:69], off offset:480
.LBB0_764:
	v_lshrrev_b32_e32 v77, 2, v71
	v_lshl_add_u32 v78, v71, 10, 0
	v_bitop3_b32 v79, v77, v70, 30 bitop3:0x6c
	v_or_b32_e32 v74, 1, v70
	s_waitcnt vmcnt(0)
	v_mul_f32_e32 v60, v60, v80
	v_lshl_add_u32 v79, v79, 2, v78
	ds_write_b32 v79, v60
	v_mul_f32_e32 v60, v61, v80
	v_bitop3_b32 v61, v77, v74, 30 bitop3:0x6c
	v_or_b32_e32 v73, 2, v70
	v_lshl_add_u32 v61, v61, 2, v78
	ds_write_b32 v61, v60
	v_bitop3_b32 v61, v77, v73, 30 bitop3:0x6c
	v_or_b32_e32 v72, 3, v70
	v_mul_f32_e32 v60, v62, v80
	v_lshl_add_u32 v61, v61, 2, v78
	ds_write_b32 v61, v60
	v_bitop3_b32 v61, v77, v72, 30 bitop3:0x6c
	v_cndmask_b32_e64 v62, 0, 1, s[10:11]
	v_mul_f32_e32 v60, v63, v80
	v_lshl_add_u32 v61, v61, 2, v78
	v_cmp_ne_u32_e64 s[6:7], 1, v62
	s_andn2_b64 vcc, exec, s[10:11]
	ds_write_b32 v61, v60
	s_cbranch_vccnz .LBB0_766
.LBB0_766:
	v_add_u32_e32 v60, 8, v71
	v_lshrrev_b32_e32 v61, 2, v60
	v_lshl_add_u32 v60, v60, 10, 0
	v_bitop3_b32 v62, v61, v70, 30 bitop3:0x6c
	s_waitcnt vmcnt(0)
	v_mul_f32_e32 v56, v56, v81
	v_lshl_add_u32 v62, v62, 2, v60
	ds_write_b32 v62, v56
	v_mul_f32_e32 v56, v57, v81
	v_bitop3_b32 v57, v61, v74, 30 bitop3:0x6c
	v_lshl_add_u32 v57, v57, 2, v60
	ds_write_b32 v57, v56
	v_bitop3_b32 v57, v61, v73, 30 bitop3:0x6c
	v_mul_f32_e32 v56, v58, v81
	v_lshl_add_u32 v57, v57, 2, v60
	ds_write_b32 v57, v56
	v_bitop3_b32 v57, v61, v72, 30 bitop3:0x6c
	v_mul_f32_e32 v56, v59, v81
	v_lshl_add_u32 v57, v57, 2, v60
	ds_write_b32 v57, v56
	v_mov_b32_e32 v56, 1.0
	s_and_b64 vcc, exec, s[6:7]
	v_mov_b32_e32 v57, 1.0
	s_cbranch_vccnz .LBB0_768
.LBB0_768:
	v_add_u32_e32 v58, 16, v71
	v_lshrrev_b32_e32 v59, 2, v58
	v_lshl_add_u32 v58, v58, 10, 0
	v_bitop3_b32 v60, v59, v70, 30 bitop3:0x6c
	s_waitcnt vmcnt(0)
	v_mul_f32_e32 v52, v52, v82
	v_lshl_add_u32 v60, v60, 2, v58
	ds_write_b32 v60, v52
	v_mul_f32_e32 v52, v53, v82
	v_bitop3_b32 v53, v59, v74, 30 bitop3:0x6c
	v_lshl_add_u32 v53, v53, 2, v58
	ds_write_b32 v53, v52
	v_bitop3_b32 v53, v59, v73, 30 bitop3:0x6c
	v_mul_f32_e32 v52, v54, v82
	v_lshl_add_u32 v53, v53, 2, v58
	ds_write_b32 v53, v52
	v_bitop3_b32 v53, v59, v72, 30 bitop3:0x6c
	v_mul_f32_e32 v52, v55, v82
	v_lshl_add_u32 v53, v53, 2, v58
	s_and_b64 vcc, exec, s[6:7]
	ds_write_b32 v53, v52
	s_cbranch_vccnz .LBB0_770
; #define LAS __attribute__((address_space(3)))
; __device__ __forceinline__ void transpose_tile(const float* src, int ld, int K, const float* gvec, bf16_t* dst, int kt, int nt, int mode, LAS float* tl) {
;     ...
;     for (int i = 0; i < 16; ++i) {
;         const int row = (tid >> 6) + 8 * i;
;         const float g = gvec ? gvec[k0 + row] : 1.f;
;         const int sw = ((row >> 3) & 15) << 1; LAS float* q = tl + row * 256;
;         q[(j) ^ sw] = v[i].x * g; q[(j + 1) ^ sw] = v[i].y * g; q[(j + 2) ^ sw] = v[i].z * g; q[(j + 3) ^ sw] = v[i].w * g;
;     }
.LBB0_770:
	v_add_u32_e32 v52, 24, v71
	v_lshrrev_b32_e32 v53, 2, v52
	v_lshl_add_u32 v52, v52, 10, 0
	v_bitop3_b32 v54, v53, v70, 30 bitop3:0x6c
	s_waitcnt vmcnt(0)
	v_mul_f32_e32 v48, v48, v83
	v_lshl_add_u32 v54, v54, 2, v52
	ds_write_b32 v54, v48
	v_mul_f32_e32 v48, v49, v83
	v_bitop3_b32 v49, v53, v74, 30 bitop3:0x6c
	v_lshl_add_u32 v49, v49, 2, v52
	ds_write_b32 v49, v48
	v_bitop3_b32 v49, v53, v73, 30 bitop3:0x6c
	v_mul_f32_e32 v48, v50, v83
	v_lshl_add_u32 v49, v49, 2, v52
	ds_write_b32 v49, v48
	v_bitop3_b32 v49, v53, v72, 30 bitop3:0x6c
	v_mul_f32_e32 v48, v51, v83
	v_lshl_add_u32 v49, v49, 2, v52
	ds_write_b32 v49, v48
	v_mov_b32_e32 v48, 1.0
	s_and_b64 vcc, exec, s[6:7]
	v_mov_b32_e32 v49, 1.0
	s_cbranch_vccnz .LBB0_772
.LBB0_772:
	v_add_u32_e32 v50, 32, v71
	v_lshrrev_b32_e32 v51, 2, v50
	v_lshl_add_u32 v50, v50, 10, 0
	v_bitop3_b32 v52, v51, v70, 30 bitop3:0x6c
	s_waitcnt vmcnt(0)
	v_mul_f32_e32 v44, v44, v84
	v_lshl_add_u32 v52, v52, 2, v50
	ds_write_b32 v52, v44
	v_mul_f32_e32 v44, v45, v84
	v_bitop3_b32 v45, v51, v74, 30 bitop3:0x6c
	v_lshl_add_u32 v45, v45, 2, v50
	ds_write_b32 v45, v44
	v_bitop3_b32 v45, v51, v73, 30 bitop3:0x6c
	v_mul_f32_e32 v44, v46, v84
	v_lshl_add_u32 v45, v45, 2, v50
	ds_write_b32 v45, v44
	v_bitop3_b32 v45, v51, v72, 30 bitop3:0x6c
	v_mul_f32_e32 v44, v47, v84
	v_lshl_add_u32 v45, v45, 2, v50
	s_and_b64 vcc, exec, s[6:7]
	ds_write_b32 v45, v44
	s_cbranch_vccnz .LBB0_774
.LBB0_774:
	v_add_u32_e32 v44, 40, v71
	v_lshrrev_b32_e32 v45, 2, v44
	v_lshl_add_u32 v44, v44, 10, 0
	v_bitop3_b32 v46, v45, v70, 30 bitop3:0x6c
	s_waitcnt vmcnt(0)
	v_mul_f32_e32 v40, v40, v85
	v_lshl_add_u32 v46, v46, 2, v44
	ds_write_b32 v46, v40
	v_mul_f32_e32 v40, v41, v85
	v_bitop3_b32 v41, v45, v74, 30 bitop3:0x6c
	v_lshl_add_u32 v41, v41, 2, v44
	ds_write_b32 v41, v40
	v_bitop3_b32 v41, v45, v73, 30 bitop3:0x6c
	v_mul_f32_e32 v40, v42, v85
	v_lshl_add_u32 v41, v41, 2, v44
	ds_write_b32 v41, v40
	v_bitop3_b32 v41, v45, v72, 30 bitop3:0x6c
	v_mul_f32_e32 v40, v43, v85
	v_lshl_add_u32 v41, v41, 2, v44
	ds_write_b32 v41, v40
	v_mov_b32_e32 v40, 1.0
	s_and_b64 vcc, exec, s[6:7]
	v_mov_b32_e32 v41, 1.0
	s_cbranch_vccnz .LBB0_776
.LBB0_776:
	v_add_u32_e32 v42, 48, v71
	v_lshrrev_b32_e32 v43, 2, v42
	v_lshl_add_u32 v42, v42, 10, 0
	v_bitop3_b32 v44, v43, v70, 30 bitop3:0x6c
	s_waitcnt vmcnt(0)
	v_mul_f32_e32 v36, v36, v86
	v_lshl_add_u32 v44, v44, 2, v42
	ds_write_b32 v44, v36
	v_mul_f32_e32 v36, v37, v86
	v_bitop3_b32 v37, v43, v74, 30 bitop3:0x6c
	v_lshl_add_u32 v37, v37, 2, v42
	ds_write_b32 v37, v36
	v_bitop3_b32 v37, v43, v73, 30 bitop3:0x6c
	v_mul_f32_e32 v36, v38, v86
	v_lshl_add_u32 v37, v37, 2, v42
	ds_write_b32 v37, v36
	v_bitop3_b32 v37, v43, v72, 30 bitop3:0x6c
	v_mul_f32_e32 v36, v39, v86
	v_lshl_add_u32 v37, v37, 2, v42
	s_and_b64 vcc, exec, s[6:7]
	ds_write_b32 v37, v36
	s_cbranch_vccnz .LBB0_778
.LBB0_778:
	v_add_u32_e32 v36, 56, v71
	v_lshrrev_b32_e32 v37, 2, v36
	v_lshl_add_u32 v36, v36, 10, 0
	v_bitop3_b32 v38, v37, v70, 30 bitop3:0x6c
	s_waitcnt vmcnt(0)
	v_mul_f32_e32 v32, v32, v87
	v_lshl_add_u32 v38, v38, 2, v36
	ds_write_b32 v38, v32
	v_mul_f32_e32 v32, v33, v87
	v_bitop3_b32 v33, v37, v74, 30 bitop3:0x6c
	v_lshl_add_u32 v33, v33, 2, v36
	ds_write_b32 v33, v32
	v_bitop3_b32 v33, v37, v73, 30 bitop3:0x6c
	v_mul_f32_e32 v32, v34, v87
	v_lshl_add_u32 v33, v33, 2, v36
	ds_write_b32 v33, v32
	v_bitop3_b32 v33, v37, v72, 30 bitop3:0x6c
	v_mul_f32_e32 v32, v35, v87
	v_lshl_add_u32 v33, v33, 2, v36
	ds_write_b32 v33, v32
	v_mov_b32_e32 v32, 1.0
	s_and_b64 vcc, exec, s[6:7]
	v_mov_b32_e32 v33, 1.0
	s_cbranch_vccnz .LBB0_780
.LBB0_780:
	v_add_u32_e32 v34, 64, v71
	v_lshrrev_b32_e32 v35, 2, v34
	v_lshl_add_u32 v34, v34, 10, 0
	v_bitop3_b32 v36, v35, v70, 30 bitop3:0x6c
	s_waitcnt vmcnt(0)
	v_mul_f32_e32 v28, v28, v88
	v_lshl_add_u32 v36, v36, 2, v34
	ds_write_b32 v36, v28
	v_mul_f32_e32 v28, v29, v88
	v_bitop3_b32 v29, v35, v74, 30 bitop3:0x6c
	v_lshl_add_u32 v29, v29, 2, v34
	ds_write_b32 v29, v28
	v_bitop3_b32 v29, v35, v73, 30 bitop3:0x6c
	v_mul_f32_e32 v28, v30, v88
	v_lshl_add_u32 v29, v29, 2, v34
	ds_write_b32 v29, v28
	v_bitop3_b32 v29, v35, v72, 30 bitop3:0x6c
	v_mul_f32_e32 v28, v31, v88
	v_lshl_add_u32 v29, v29, 2, v34
	s_and_b64 vcc, exec, s[6:7]
	ds_write_b32 v29, v28
	s_cbranch_vccnz .LBB0_782
; #define LAS __attribute__((address_space(3)))
; __device__ __forceinline__ void transpose_tile(const float* src, int ld, int K, const float* gvec, bf16_t* dst, int kt, int nt, int mode, LAS float* tl) {
;     ...
;     for (int i = 0; i < 16; ++i) {
;         const int row = (tid >> 6) + 8 * i;
;         const float g = gvec ? gvec[k0 + row] : 1.f;
;         const int sw = ((row >> 3) & 15) << 1; LAS float* q = tl + row * 256;
;         q[(j) ^ sw] = v[i].x * g; q[(j + 1) ^ sw] = v[i].y * g; q[(j + 2) ^ sw] = v[i].z * g; q[(j + 3) ^ sw] = v[i].w * g;
;     }
.LBB0_782:
	v_add_u32_e32 v28, 0x48, v71
	v_lshrrev_b32_e32 v29, 2, v28
	v_lshl_add_u32 v28, v28, 10, 0
	v_bitop3_b32 v30, v29, v70, 30 bitop3:0x6c
	s_waitcnt vmcnt(0)
	v_mul_f32_e32 v24, v24, v89
	v_lshl_add_u32 v30, v30, 2, v28
	ds_write_b32 v30, v24
	v_mul_f32_e32 v24, v25, v89
	v_bitop3_b32 v25, v29, v74, 30 bitop3:0x6c
	v_lshl_add_u32 v25, v25, 2, v28
	ds_write_b32 v25, v24
	v_bitop3_b32 v25, v29, v73, 30 bitop3:0x6c
	v_mul_f32_e32 v24, v26, v89
	v_lshl_add_u32 v25, v25, 2, v28
	ds_write_b32 v25, v24
	v_bitop3_b32 v25, v29, v72, 30 bitop3:0x6c
	v_mul_f32_e32 v24, v27, v89
	v_lshl_add_u32 v25, v25, 2, v28
	ds_write_b32 v25, v24
	v_mov_b32_e32 v24, 1.0
	s_and_b64 vcc, exec, s[6:7]
	v_mov_b32_e32 v25, 1.0
	s_cbranch_vccnz .LBB0_784
.LBB0_784:
	v_add_u32_e32 v26, 0x50, v71
	v_lshrrev_b32_e32 v27, 2, v26
	v_lshl_add_u32 v26, v26, 10, 0
	v_bitop3_b32 v28, v27, v70, 30 bitop3:0x6c
	s_waitcnt vmcnt(0)
	v_mul_f32_e32 v20, v20, v90
	v_lshl_add_u32 v28, v28, 2, v26
	ds_write_b32 v28, v20
	v_mul_f32_e32 v20, v21, v90
	v_bitop3_b32 v21, v27, v74, 30 bitop3:0x6c
	v_lshl_add_u32 v21, v21, 2, v26
	ds_write_b32 v21, v20
	v_bitop3_b32 v21, v27, v73, 30 bitop3:0x6c
	v_mul_f32_e32 v20, v22, v90
	v_lshl_add_u32 v21, v21, 2, v26
	ds_write_b32 v21, v20
	v_bitop3_b32 v21, v27, v72, 30 bitop3:0x6c
	v_mul_f32_e32 v20, v23, v90
	v_lshl_add_u32 v21, v21, 2, v26
	s_and_b64 vcc, exec, s[6:7]
	ds_write_b32 v21, v20
	s_cbranch_vccnz .LBB0_786
.LBB0_786:
	v_add_u32_e32 v20, 0x58, v71
	v_lshrrev_b32_e32 v21, 2, v20
	v_lshl_add_u32 v20, v20, 10, 0
	v_bitop3_b32 v22, v21, v70, 30 bitop3:0x6c
	s_waitcnt vmcnt(0)
	v_mul_f32_e32 v16, v16, v91
	v_lshl_add_u32 v22, v22, 2, v20
	ds_write_b32 v22, v16
	v_mul_f32_e32 v16, v17, v91
	v_bitop3_b32 v17, v21, v74, 30 bitop3:0x6c
	v_lshl_add_u32 v17, v17, 2, v20
	ds_write_b32 v17, v16
	v_bitop3_b32 v17, v21, v73, 30 bitop3:0x6c
	v_mul_f32_e32 v16, v18, v91
	v_lshl_add_u32 v17, v17, 2, v20
	ds_write_b32 v17, v16
	v_bitop3_b32 v17, v21, v72, 30 bitop3:0x6c
	v_mul_f32_e32 v16, v19, v91
	v_lshl_add_u32 v17, v17, 2, v20
	ds_write_b32 v17, v16
	v_mov_b32_e32 v16, 1.0
	s_and_b64 vcc, exec, s[6:7]
	v_mov_b32_e32 v17, 1.0
	s_cbranch_vccnz .LBB0_788
.LBB0_788:
	v_add_u32_e32 v18, 0x60, v71
	v_lshrrev_b32_e32 v19, 2, v18
	v_lshl_add_u32 v18, v18, 10, 0
	v_bitop3_b32 v20, v19, v70, 30 bitop3:0x6c
	s_waitcnt vmcnt(0)
	v_mul_f32_e32 v12, v12, v92
	v_lshl_add_u32 v20, v20, 2, v18
	ds_write_b32 v20, v12
	v_mul_f32_e32 v12, v13, v92
	v_bitop3_b32 v13, v19, v74, 30 bitop3:0x6c
	v_lshl_add_u32 v13, v13, 2, v18
	ds_write_b32 v13, v12
	v_bitop3_b32 v13, v19, v73, 30 bitop3:0x6c
	v_mul_f32_e32 v12, v14, v92
	v_lshl_add_u32 v13, v13, 2, v18
	ds_write_b32 v13, v12
	v_bitop3_b32 v13, v19, v72, 30 bitop3:0x6c
	v_mul_f32_e32 v12, v15, v92
	v_lshl_add_u32 v13, v13, 2, v18
	s_and_b64 vcc, exec, s[6:7]
	ds_write_b32 v13, v12
	s_cbranch_vccnz .LBB0_790
.LBB0_790:
	v_add_u32_e32 v12, 0x68, v71
	v_lshrrev_b32_e32 v13, 2, v12
	v_lshl_add_u32 v12, v12, 10, 0
	v_bitop3_b32 v14, v13, v70, 30 bitop3:0x6c
	s_waitcnt vmcnt(0)
	v_mul_f32_e32 v8, v8, v93
	v_lshl_add_u32 v14, v14, 2, v12
	ds_write_b32 v14, v8
	v_mul_f32_e32 v8, v9, v93
	v_bitop3_b32 v9, v13, v74, 30 bitop3:0x6c
	v_lshl_add_u32 v9, v9, 2, v12
	ds_write_b32 v9, v8
	v_bitop3_b32 v9, v13, v73, 30 bitop3:0x6c
	v_mul_f32_e32 v8, v10, v93
	v_lshl_add_u32 v9, v9, 2, v12
	ds_write_b32 v9, v8
	v_bitop3_b32 v9, v13, v72, 30 bitop3:0x6c
	v_mul_f32_e32 v8, v11, v93
	v_lshl_add_u32 v9, v9, 2, v12
	ds_write_b32 v9, v8
	v_mov_b32_e32 v8, 1.0
	s_and_b64 vcc, exec, s[6:7]
	v_mov_b32_e32 v9, 1.0
	s_cbranch_vccnz .LBB0_792
.LBB0_792:
	v_add_u32_e32 v10, 0x70, v71
	v_lshrrev_b32_e32 v11, 2, v10
	v_lshl_add_u32 v10, v10, 10, 0
	v_bitop3_b32 v12, v11, v70, 30 bitop3:0x6c
	s_waitcnt vmcnt(0)
	v_mul_f32_e32 v4, v4, v94
	v_lshl_add_u32 v12, v12, 2, v10
	ds_write_b32 v12, v4
	v_mul_f32_e32 v4, v5, v94
	v_bitop3_b32 v5, v11, v74, 30 bitop3:0x6c
	v_lshl_add_u32 v5, v5, 2, v10
	ds_write_b32 v5, v4
	v_bitop3_b32 v5, v11, v73, 30 bitop3:0x6c
	v_mul_f32_e32 v4, v6, v94
	v_lshl_add_u32 v5, v5, 2, v10
	ds_write_b32 v5, v4
	v_bitop3_b32 v5, v11, v72, 30 bitop3:0x6c
	v_mul_f32_e32 v4, v7, v94
	v_lshl_add_u32 v5, v5, 2, v10
	s_and_b64 vcc, exec, s[6:7]
	ds_write_b32 v5, v4
	s_cbranch_vccnz .LBB0_739
	s_branch .LBB0_739
